# adds: P2 decay-mask stage reads the 16 cumulative-decay values with 4 ds_read_b128 up front instead of 16 serial ds_read_b32
# speedup vs baseline: 1.0084x; 1.0006x over previous
; __device__ __forceinline__ unsigned f2bf(float f) { unsigned u = __float_as_uint(f); return (u + 0x7fffu + ((u >> 16) & 1u)) >> 16; }
; __device__ __forceinline__ int perm16(int p) { return (p & 3) + ((p >> 2) & 1) * 8 + ((p >> 3) & 1) * 4; }
; __device__ __forceinline__ void gdn_prep_item(const Params& p, unsigned char* lds, int item, u32x4 (&raw)[3][2][4], float& gpre, float& bpre, int next_item) {
;     ...
;         const int j = 32 * tj + r32; const float gcj = gcs[j];
;         const int posj = (j & ~15) + perm16(j & 15);
;         int ib = 32 * ti + 4 * g; asm volatile("" : "+v"(ib));
;         const float* gci_p = gcs + ib; const float* bti_p = bets + ib;
; #pragma unroll
;         for (int r = 0; r < 16; ++r) { const int io = (r & 3) + 8 * (r >> 2); const int i = ib + io;
;             const float gi = gci_p[io], bt = bti_p[io];
;             const float dec = __expf(fminf(gi - gcj, 0.f));
;             const float lv = (i > j) ? acc[r] * bt * dec : 0.f, av = (i >= j) ? acc[r] * dec : 0.f;
;             if (mat == 0) Lm[i * 64 + j] = -lv;
;             else Aml[i * 72 + posj] = (bf16_t)f2bf(av); }
.LBB0_108:
	s_or_b64 exec, exec, s[20:21]
	v_mov_b32_e32 v17, v151
	ds_read_b32 v18, v150
	s_nop 0
	v_lshlrev_b32_e32 v174, 2, v17
	v_add_u32_e32 v19, 0, v174
	v_add_u32_e32 v19, 0x23c00, v19
	ds_read_b128 v[232:235], v19
	ds_read_b128 v[236:239], v19 offset:32
	ds_read_b128 v[240:243], v19 offset:64
	ds_read_b128 v[244:247], v19 offset:96
	s_waitcnt lgkmcnt(0)
	v_sub_f32_e32 v175, v232, v18
	v_min_f32_e32 v175, 0, v175
	v_mul_f32_e32 v175, 0x3fb8aa3b, v175
	v_exp_f32_e32 v175, v175
	s_and_saveexec_b64 s[20:21], s[18:19]
	s_xor_b64 s[20:21], exec, s[20:21]
	s_cbranch_execz .LBB0_110
	v_mul_f32_e32 v0, v0, v175
	v_cmp_ge_i32_e32 vcc, v17, v148
	v_mad_u64_u32 v[176:177], s[22:23], v17, s31, v[122:123]
	s_nop 0
	v_cndmask_b32_e32 v0, 0, v0, vcc
	v_bfe_u32 v175, v0, 16, 1
	v_add3_u32 v0, v0, v175, s96
	ds_write_b16_d16_hi v176, v0

; __device__ __forceinline__ unsigned f2bf(float f) { unsigned u = __float_as_uint(f); return (u + 0x7fffu + ((u >> 16) & 1u)) >> 16; }
; __device__ __forceinline__ void gdn_prep_item(const Params& p, unsigned char* lds, int item, u32x4 (&raw)[3][2][4], float& gpre, float& bpre, int next_item) {
;     ...
;         for (int r = 0; r < 16; ++r) { const int io = (r & 3) + 8 * (r >> 2); const int i = ib + io;
;             const float gi = gci_p[io], bt = bti_p[io];
;             const float dec = __expf(fminf(gi - gcj, 0.f));
;             const float lv = (i > j) ? acc[r] * bt * dec : 0.f, av = (i >= j) ? acc[r] * dec : 0.f;
;             if (mat == 0) Lm[i * 64 + j] = -lv;
;             else Aml[i * 72 + posj] = (bf16_t)f2bf(av); }
.LBB0_112:
	s_or_b64 exec, exec, s[20:21]
	v_sub_f32_e32 v0, v233, v18
	v_min_f32_e32 v0, 0, v0
	v_mul_f32_e32 v0, 0x3fb8aa3b, v0
	v_exp_f32_e32 v175, v0
	v_add_u32_e32 v0, 1, v17
	s_and_saveexec_b64 s[20:21], s[18:19]
	s_xor_b64 s[20:21], exec, s[20:21]
	s_cbranch_execz .LBB0_114
	v_mul_f32_e32 v1, v1, v175
	v_cmp_ge_i32_e32 vcc, v0, v148
	s_nop 1
	v_cndmask_b32_e32 v1, 0, v1, vcc
	v_bfe_u32 v175, v1, 16, 1
	v_add3_u32 v175, v1, v175, s96
	v_mad_u64_u32 v[0:1], s[22:23], v0, s31, v[122:123]
	ds_write_b16_d16_hi v0, v175

; __device__ __forceinline__ unsigned f2bf(float f) { unsigned u = __float_as_uint(f); return (u + 0x7fffu + ((u >> 16) & 1u)) >> 16; }
; __device__ __forceinline__ void gdn_prep_item(const Params& p, unsigned char* lds, int item, u32x4 (&raw)[3][2][4], float& gpre, float& bpre, int next_item) {
;     ...
;         for (int r = 0; r < 16; ++r) { const int io = (r & 3) + 8 * (r >> 2); const int i = ib + io;
;             const float gi = gci_p[io], bt = bti_p[io];
;             const float dec = __expf(fminf(gi - gcj, 0.f));
;             const float lv = (i > j) ? acc[r] * bt * dec : 0.f, av = (i >= j) ? acc[r] * dec : 0.f;
;             if (mat == 0) Lm[i * 64 + j] = -lv;
;             else Aml[i * 72 + posj] = (bf16_t)f2bf(av); }
.LBB0_116:
	s_or_b64 exec, exec, s[20:21]
	v_sub_f32_e32 v0, v234, v18
	v_min_f32_e32 v0, 0, v0
	v_mul_f32_e32 v0, 0x3fb8aa3b, v0
	v_exp_f32_e32 v1, v0
	v_add_u32_e32 v0, 2, v17
	s_and_saveexec_b64 s[20:21], s[18:19]
	s_xor_b64 s[20:21], exec, s[20:21]
	s_cbranch_execz .LBB0_118
	v_mul_f32_e32 v1, v2, v1
	v_cmp_ge_i32_e32 vcc, v0, v148
	s_nop 1
	v_cndmask_b32_e32 v1, 0, v1, vcc
	v_bfe_u32 v2, v1, 16, 1
	v_add3_u32 v2, v1, v2, s96
	v_mad_u64_u32 v[0:1], s[22:23], v0, s31, v[122:123]
	ds_write_b16_d16_hi v0, v2

; __device__ __forceinline__ unsigned f2bf(float f) { unsigned u = __float_as_uint(f); return (u + 0x7fffu + ((u >> 16) & 1u)) >> 16; }
; __device__ __forceinline__ void gdn_prep_item(const Params& p, unsigned char* lds, int item, u32x4 (&raw)[3][2][4], float& gpre, float& bpre, int next_item) {
;     ...
;         for (int r = 0; r < 16; ++r) { const int io = (r & 3) + 8 * (r >> 2); const int i = ib + io;
;             const float gi = gci_p[io], bt = bti_p[io];
;             const float dec = __expf(fminf(gi - gcj, 0.f));
;             const float lv = (i > j) ? acc[r] * bt * dec : 0.f, av = (i >= j) ? acc[r] * dec : 0.f;
;             if (mat == 0) Lm[i * 64 + j] = -lv;
;             else Aml[i * 72 + posj] = (bf16_t)f2bf(av); }
.LBB0_120:
	s_or_b64 exec, exec, s[20:21]
	v_sub_f32_e32 v0, v235, v18
	v_min_f32_e32 v0, 0, v0
	v_mul_f32_e32 v0, 0x3fb8aa3b, v0
	v_exp_f32_e32 v1, v0
	v_add_u32_e32 v0, 3, v17
	s_and_saveexec_b64 s[20:21], s[18:19]
	s_xor_b64 s[20:21], exec, s[20:21]
	s_cbranch_execz .LBB0_122
	v_mul_f32_e32 v1, v3, v1
	v_cmp_ge_i32_e32 vcc, v0, v148
	s_nop 1
	v_cndmask_b32_e32 v1, 0, v1, vcc
	v_bfe_u32 v2, v1, 16, 1
	v_add3_u32 v2, v1, v2, s96
	v_mad_u64_u32 v[0:1], s[22:23], v0, s31, v[122:123]
	ds_write_b16_d16_hi v0, v2

; __device__ __forceinline__ unsigned f2bf(float f) { unsigned u = __float_as_uint(f); return (u + 0x7fffu + ((u >> 16) & 1u)) >> 16; }
; __device__ __forceinline__ void gdn_prep_item(const Params& p, unsigned char* lds, int item, u32x4 (&raw)[3][2][4], float& gpre, float& bpre, int next_item) {
;     ...
;         for (int r = 0; r < 16; ++r) { const int io = (r & 3) + 8 * (r >> 2); const int i = ib + io;
;             const float gi = gci_p[io], bt = bti_p[io];
;             const float dec = __expf(fminf(gi - gcj, 0.f));
;             const float lv = (i > j) ? acc[r] * bt * dec : 0.f, av = (i >= j) ? acc[r] * dec : 0.f;
;             if (mat == 0) Lm[i * 64 + j] = -lv;
;             else Aml[i * 72 + posj] = (bf16_t)f2bf(av); }
.LBB0_124:
	s_or_b64 exec, exec, s[20:21]
	v_sub_f32_e32 v0, v236, v18
	v_min_f32_e32 v0, 0, v0
	v_mul_f32_e32 v0, 0x3fb8aa3b, v0
	v_exp_f32_e32 v1, v0
	v_add_u32_e32 v0, 8, v17
	s_and_saveexec_b64 s[20:21], s[18:19]
	s_xor_b64 s[20:21], exec, s[20:21]
	s_cbranch_execz .LBB0_126
	v_mul_f32_e32 v1, v4, v1
	v_cmp_ge_i32_e32 vcc, v0, v148
	s_nop 1
	v_cndmask_b32_e32 v1, 0, v1, vcc
	v_bfe_u32 v2, v1, 16, 1
	v_add3_u32 v2, v1, v2, s96
	v_mad_u64_u32 v[0:1], s[22:23], v0, s31, v[122:123]
	ds_write_b16_d16_hi v0, v2

; __device__ __forceinline__ unsigned f2bf(float f) { unsigned u = __float_as_uint(f); return (u + 0x7fffu + ((u >> 16) & 1u)) >> 16; }
; __device__ __forceinline__ void gdn_prep_item(const Params& p, unsigned char* lds, int item, u32x4 (&raw)[3][2][4], float& gpre, float& bpre, int next_item) {
;     ...
;         for (int r = 0; r < 16; ++r) { const int io = (r & 3) + 8 * (r >> 2); const int i = ib + io;
;             const float gi = gci_p[io], bt = bti_p[io];
;             const float dec = __expf(fminf(gi - gcj, 0.f));
;             const float lv = (i > j) ? acc[r] * bt * dec : 0.f, av = (i >= j) ? acc[r] * dec : 0.f;
;             if (mat == 0) Lm[i * 64 + j] = -lv;
;             else Aml[i * 72 + posj] = (bf16_t)f2bf(av); }
.LBB0_128:
	s_or_b64 exec, exec, s[20:21]
	v_sub_f32_e32 v0, v237, v18
	v_min_f32_e32 v0, 0, v0
	v_mul_f32_e32 v0, 0x3fb8aa3b, v0
	v_exp_f32_e32 v1, v0
	v_add_u32_e32 v0, 9, v17
	s_and_saveexec_b64 s[20:21], s[18:19]
	s_xor_b64 s[20:21], exec, s[20:21]
	s_cbranch_execz .LBB0_130
	v_mul_f32_e32 v1, v5, v1
	v_cmp_ge_i32_e32 vcc, v0, v148
	s_nop 1
	v_cndmask_b32_e32 v1, 0, v1, vcc
	v_bfe_u32 v2, v1, 16, 1
	v_add3_u32 v2, v1, v2, s96
	v_mad_u64_u32 v[0:1], s[22:23], v0, s31, v[122:123]
	ds_write_b16_d16_hi v0, v2

; __device__ __forceinline__ unsigned f2bf(float f) { unsigned u = __float_as_uint(f); return (u + 0x7fffu + ((u >> 16) & 1u)) >> 16; }
; __device__ __forceinline__ void gdn_prep_item(const Params& p, unsigned char* lds, int item, u32x4 (&raw)[3][2][4], float& gpre, float& bpre, int next_item) {
;     ...
;         for (int r = 0; r < 16; ++r) { const int io = (r & 3) + 8 * (r >> 2); const int i = ib + io;
;             const float gi = gci_p[io], bt = bti_p[io];
;             const float dec = __expf(fminf(gi - gcj, 0.f));
;             const float lv = (i > j) ? acc[r] * bt * dec : 0.f, av = (i >= j) ? acc[r] * dec : 0.f;
;             if (mat == 0) Lm[i * 64 + j] = -lv;
;             else Aml[i * 72 + posj] = (bf16_t)f2bf(av); }
.LBB0_132:
	s_or_b64 exec, exec, s[20:21]
	v_sub_f32_e32 v0, v238, v18
	v_min_f32_e32 v0, 0, v0
	v_mul_f32_e32 v0, 0x3fb8aa3b, v0
	v_exp_f32_e32 v1, v0
	v_add_u32_e32 v0, 10, v17
	s_and_saveexec_b64 s[20:21], s[18:19]
	s_xor_b64 s[20:21], exec, s[20:21]
	s_cbranch_execz .LBB0_134
	v_mul_f32_e32 v1, v6, v1
	v_cmp_ge_i32_e32 vcc, v0, v148
	s_nop 1
	v_cndmask_b32_e32 v1, 0, v1, vcc
	v_bfe_u32 v2, v1, 16, 1
	v_add3_u32 v2, v1, v2, s96
	v_mad_u64_u32 v[0:1], s[22:23], v0, s31, v[122:123]
	ds_write_b16_d16_hi v0, v2

; __device__ __forceinline__ unsigned f2bf(float f) { unsigned u = __float_as_uint(f); return (u + 0x7fffu + ((u >> 16) & 1u)) >> 16; }
; __device__ __forceinline__ void gdn_prep_item(const Params& p, unsigned char* lds, int item, u32x4 (&raw)[3][2][4], float& gpre, float& bpre, int next_item) {
;     ...
;         for (int r = 0; r < 16; ++r) { const int io = (r & 3) + 8 * (r >> 2); const int i = ib + io;
;             const float gi = gci_p[io], bt = bti_p[io];
;             const float dec = __expf(fminf(gi - gcj, 0.f));
;             const float lv = (i > j) ? acc[r] * bt * dec : 0.f, av = (i >= j) ? acc[r] * dec : 0.f;
;             if (mat == 0) Lm[i * 64 + j] = -lv;
;             else Aml[i * 72 + posj] = (bf16_t)f2bf(av); }
.LBB0_136:
	s_or_b64 exec, exec, s[20:21]
	v_sub_f32_e32 v0, v239, v18
	v_min_f32_e32 v0, 0, v0
	v_mul_f32_e32 v0, 0x3fb8aa3b, v0
	v_exp_f32_e32 v1, v0
	v_add_u32_e32 v0, 11, v17
	s_and_saveexec_b64 s[20:21], s[18:19]
	s_xor_b64 s[20:21], exec, s[20:21]
	s_cbranch_execz .LBB0_138
	v_mul_f32_e32 v1, v7, v1
	v_cmp_ge_i32_e32 vcc, v0, v148
	s_nop 1
	v_cndmask_b32_e32 v1, 0, v1, vcc
	v_bfe_u32 v2, v1, 16, 1
	v_add3_u32 v2, v1, v2, s96
	v_mad_u64_u32 v[0:1], s[22:23], v0, s31, v[122:123]
	ds_write_b16_d16_hi v0, v2

; __device__ __forceinline__ unsigned f2bf(float f) { unsigned u = __float_as_uint(f); return (u + 0x7fffu + ((u >> 16) & 1u)) >> 16; }
; __device__ __forceinline__ void gdn_prep_item(const Params& p, unsigned char* lds, int item, u32x4 (&raw)[3][2][4], float& gpre, float& bpre, int next_item) {
;     ...
;         for (int r = 0; r < 16; ++r) { const int io = (r & 3) + 8 * (r >> 2); const int i = ib + io;
;             const float gi = gci_p[io], bt = bti_p[io];
;             const float dec = __expf(fminf(gi - gcj, 0.f));
;             const float lv = (i > j) ? acc[r] * bt * dec : 0.f, av = (i >= j) ? acc[r] * dec : 0.f;
;             if (mat == 0) Lm[i * 64 + j] = -lv;
;             else Aml[i * 72 + posj] = (bf16_t)f2bf(av); }
.LBB0_140:
	s_or_b64 exec, exec, s[20:21]
	v_sub_f32_e32 v0, v240, v18
	v_min_f32_e32 v0, 0, v0
	v_mul_f32_e32 v0, 0x3fb8aa3b, v0
	v_exp_f32_e32 v1, v0
	v_add_u32_e32 v0, 16, v17
	s_and_saveexec_b64 s[20:21], s[18:19]
	s_xor_b64 s[20:21], exec, s[20:21]
	s_cbranch_execz .LBB0_142
	v_mul_f32_e32 v1, v8, v1
	v_cmp_ge_i32_e32 vcc, v0, v148
	s_nop 1
	v_cndmask_b32_e32 v1, 0, v1, vcc
	v_bfe_u32 v2, v1, 16, 1
	v_add3_u32 v2, v1, v2, s96
	v_mad_u64_u32 v[0:1], s[22:23], v0, s31, v[122:123]
	ds_write_b16_d16_hi v0, v2

; __device__ __forceinline__ unsigned f2bf(float f) { unsigned u = __float_as_uint(f); return (u + 0x7fffu + ((u >> 16) & 1u)) >> 16; }
; __device__ __forceinline__ void gdn_prep_item(const Params& p, unsigned char* lds, int item, u32x4 (&raw)[3][2][4], float& gpre, float& bpre, int next_item) {
;     ...
;         for (int r = 0; r < 16; ++r) { const int io = (r & 3) + 8 * (r >> 2); const int i = ib + io;
;             const float gi = gci_p[io], bt = bti_p[io];
;             const float dec = __expf(fminf(gi - gcj, 0.f));
;             const float lv = (i > j) ? acc[r] * bt * dec : 0.f, av = (i >= j) ? acc[r] * dec : 0.f;
;             if (mat == 0) Lm[i * 64 + j] = -lv;
;             else Aml[i * 72 + posj] = (bf16_t)f2bf(av); }
.LBB0_144:
	s_or_b64 exec, exec, s[20:21]
	v_sub_f32_e32 v0, v241, v18
	v_min_f32_e32 v0, 0, v0
	v_mul_f32_e32 v0, 0x3fb8aa3b, v0
	v_exp_f32_e32 v1, v0
	v_add_u32_e32 v0, 17, v17
	s_and_saveexec_b64 s[20:21], s[18:19]
	s_xor_b64 s[20:21], exec, s[20:21]
	s_cbranch_execz .LBB0_146
	v_mul_f32_e32 v1, v9, v1
	v_cmp_ge_i32_e32 vcc, v0, v148
	s_nop 1
	v_cndmask_b32_e32 v1, 0, v1, vcc
	v_bfe_u32 v2, v1, 16, 1
	v_add3_u32 v2, v1, v2, s96
	v_mad_u64_u32 v[0:1], s[22:23], v0, s31, v[122:123]
	ds_write_b16_d16_hi v0, v2

; __device__ __forceinline__ unsigned f2bf(float f) { unsigned u = __float_as_uint(f); return (u + 0x7fffu + ((u >> 16) & 1u)) >> 16; }
; __device__ __forceinline__ void gdn_prep_item(const Params& p, unsigned char* lds, int item, u32x4 (&raw)[3][2][4], float& gpre, float& bpre, int next_item) {
;     ...
;         for (int r = 0; r < 16; ++r) { const int io = (r & 3) + 8 * (r >> 2); const int i = ib + io;
;             const float gi = gci_p[io], bt = bti_p[io];
;             const float dec = __expf(fminf(gi - gcj, 0.f));
;             const float lv = (i > j) ? acc[r] * bt * dec : 0.f, av = (i >= j) ? acc[r] * dec : 0.f;
;             if (mat == 0) Lm[i * 64 + j] = -lv;
;             else Aml[i * 72 + posj] = (bf16_t)f2bf(av); }
.LBB0_148:
	s_or_b64 exec, exec, s[20:21]
	v_sub_f32_e32 v0, v242, v18
	v_min_f32_e32 v0, 0, v0
	v_mul_f32_e32 v0, 0x3fb8aa3b, v0
	v_exp_f32_e32 v1, v0
	v_add_u32_e32 v0, 18, v17
	s_and_saveexec_b64 s[20:21], s[18:19]
	s_xor_b64 s[20:21], exec, s[20:21]
	s_cbranch_execz .LBB0_150
	v_mul_f32_e32 v1, v10, v1
	v_cmp_ge_i32_e32 vcc, v0, v148
	s_nop 1
	v_cndmask_b32_e32 v1, 0, v1, vcc
	v_bfe_u32 v2, v1, 16, 1
	v_add3_u32 v2, v1, v2, s96
	v_mad_u64_u32 v[0:1], s[22:23], v0, s31, v[122:123]
	ds_write_b16_d16_hi v0, v2

; __device__ __forceinline__ unsigned f2bf(float f) { unsigned u = __float_as_uint(f); return (u + 0x7fffu + ((u >> 16) & 1u)) >> 16; }
; __device__ __forceinline__ void gdn_prep_item(const Params& p, unsigned char* lds, int item, u32x4 (&raw)[3][2][4], float& gpre, float& bpre, int next_item) {
;     ...
;         for (int r = 0; r < 16; ++r) { const int io = (r & 3) + 8 * (r >> 2); const int i = ib + io;
;             const float gi = gci_p[io], bt = bti_p[io];
;             const float dec = __expf(fminf(gi - gcj, 0.f));
;             const float lv = (i > j) ? acc[r] * bt * dec : 0.f, av = (i >= j) ? acc[r] * dec : 0.f;
;             if (mat == 0) Lm[i * 64 + j] = -lv;
;             else Aml[i * 72 + posj] = (bf16_t)f2bf(av); }
.LBB0_152:
	s_or_b64 exec, exec, s[20:21]
	v_sub_f32_e32 v0, v243, v18
	v_min_f32_e32 v0, 0, v0
	v_mul_f32_e32 v0, 0x3fb8aa3b, v0
	v_exp_f32_e32 v1, v0
	v_add_u32_e32 v0, 19, v17
	s_and_saveexec_b64 s[20:21], s[18:19]
	s_xor_b64 s[20:21], exec, s[20:21]
	s_cbranch_execz .LBB0_154
	v_mul_f32_e32 v1, v11, v1
	v_cmp_ge_i32_e32 vcc, v0, v148
	s_nop 1
	v_cndmask_b32_e32 v1, 0, v1, vcc
	v_bfe_u32 v2, v1, 16, 1
	v_add3_u32 v2, v1, v2, s96
	v_mad_u64_u32 v[0:1], s[22:23], v0, s31, v[122:123]
	ds_write_b16_d16_hi v0, v2

; __device__ __forceinline__ unsigned f2bf(float f) { unsigned u = __float_as_uint(f); return (u + 0x7fffu + ((u >> 16) & 1u)) >> 16; }
; __device__ __forceinline__ void gdn_prep_item(const Params& p, unsigned char* lds, int item, u32x4 (&raw)[3][2][4], float& gpre, float& bpre, int next_item) {
;     ...
;         for (int r = 0; r < 16; ++r) { const int io = (r & 3) + 8 * (r >> 2); const int i = ib + io;
;             const float gi = gci_p[io], bt = bti_p[io];
;             const float dec = __expf(fminf(gi - gcj, 0.f));
;             const float lv = (i > j) ? acc[r] * bt * dec : 0.f, av = (i >= j) ? acc[r] * dec : 0.f;
;             if (mat == 0) Lm[i * 64 + j] = -lv;
;             else Aml[i * 72 + posj] = (bf16_t)f2bf(av); }
.LBB0_156:
	s_or_b64 exec, exec, s[20:21]
	v_sub_f32_e32 v0, v244, v18
	v_min_f32_e32 v0, 0, v0
	v_mul_f32_e32 v0, 0x3fb8aa3b, v0
	v_exp_f32_e32 v1, v0
	v_add_u32_e32 v0, 24, v17
	s_and_saveexec_b64 s[20:21], s[18:19]
	s_xor_b64 s[20:21], exec, s[20:21]
	s_cbranch_execz .LBB0_158
	v_mul_f32_e32 v1, v12, v1
	v_cmp_ge_i32_e32 vcc, v0, v148
	s_nop 1
	v_cndmask_b32_e32 v1, 0, v1, vcc
	v_bfe_u32 v2, v1, 16, 1
	v_add3_u32 v2, v1, v2, s96
	v_mad_u64_u32 v[0:1], s[22:23], v0, s31, v[122:123]
	ds_write_b16_d16_hi v0, v2

; __device__ __forceinline__ unsigned f2bf(float f) { unsigned u = __float_as_uint(f); return (u + 0x7fffu + ((u >> 16) & 1u)) >> 16; }
; __device__ __forceinline__ void gdn_prep_item(const Params& p, unsigned char* lds, int item, u32x4 (&raw)[3][2][4], float& gpre, float& bpre, int next_item) {
;     ...
;         for (int r = 0; r < 16; ++r) { const int io = (r & 3) + 8 * (r >> 2); const int i = ib + io;
;             const float gi = gci_p[io], bt = bti_p[io];
;             const float dec = __expf(fminf(gi - gcj, 0.f));
;             const float lv = (i > j) ? acc[r] * bt * dec : 0.f, av = (i >= j) ? acc[r] * dec : 0.f;
;             if (mat == 0) Lm[i * 64 + j] = -lv;
;             else Aml[i * 72 + posj] = (bf16_t)f2bf(av); }
.LBB0_160:
	s_or_b64 exec, exec, s[20:21]
	v_sub_f32_e32 v0, v245, v18
	v_min_f32_e32 v0, 0, v0
	v_mul_f32_e32 v0, 0x3fb8aa3b, v0
	v_exp_f32_e32 v1, v0
	v_add_u32_e32 v0, 25, v17
	s_and_saveexec_b64 s[20:21], s[18:19]
	s_xor_b64 s[20:21], exec, s[20:21]
	s_cbranch_execz .LBB0_162
	v_mul_f32_e32 v1, v13, v1
	v_cmp_ge_i32_e32 vcc, v0, v148
	s_nop 1
	v_cndmask_b32_e32 v1, 0, v1, vcc
	v_bfe_u32 v2, v1, 16, 1
	v_add3_u32 v2, v1, v2, s96
	v_mad_u64_u32 v[0:1], s[22:23], v0, s31, v[122:123]
	ds_write_b16_d16_hi v0, v2

; __device__ __forceinline__ unsigned f2bf(float f) { unsigned u = __float_as_uint(f); return (u + 0x7fffu + ((u >> 16) & 1u)) >> 16; }
; __device__ __forceinline__ void gdn_prep_item(const Params& p, unsigned char* lds, int item, u32x4 (&raw)[3][2][4], float& gpre, float& bpre, int next_item) {
;     ...
;         for (int r = 0; r < 16; ++r) { const int io = (r & 3) + 8 * (r >> 2); const int i = ib + io;
;             const float gi = gci_p[io], bt = bti_p[io];
;             const float dec = __expf(fminf(gi - gcj, 0.f));
;             const float lv = (i > j) ? acc[r] * bt * dec : 0.f, av = (i >= j) ? acc[r] * dec : 0.f;
;             if (mat == 0) Lm[i * 64 + j] = -lv;
;             else Aml[i * 72 + posj] = (bf16_t)f2bf(av); }
.LBB0_164:
	s_or_b64 exec, exec, s[20:21]
	v_sub_f32_e32 v0, v246, v18
	v_min_f32_e32 v0, 0, v0
	v_mul_f32_e32 v0, 0x3fb8aa3b, v0
	v_exp_f32_e32 v1, v0
	v_add_u32_e32 v0, 26, v17
	s_and_saveexec_b64 s[20:21], s[18:19]
	s_xor_b64 s[20:21], exec, s[20:21]
	s_cbranch_execz .LBB0_166
	v_mul_f32_e32 v1, v14, v1
	v_cmp_ge_i32_e32 vcc, v0, v148
	s_nop 1
	v_cndmask_b32_e32 v1, 0, v1, vcc
	v_bfe_u32 v2, v1, 16, 1
	v_add3_u32 v2, v1, v2, s96
	v_mad_u64_u32 v[0:1], s[22:23], v0, s31, v[122:123]
	ds_write_b16_d16_hi v0, v2

; __device__ __forceinline__ unsigned f2bf(float f) { unsigned u = __float_as_uint(f); return (u + 0x7fffu + ((u >> 16) & 1u)) >> 16; }
; __device__ __forceinline__ void gdn_prep_item(const Params& p, unsigned char* lds, int item, u32x4 (&raw)[3][2][4], float& gpre, float& bpre, int next_item) {
;     ...
;         for (int r = 0; r < 16; ++r) { const int io = (r & 3) + 8 * (r >> 2); const int i = ib + io;
;             const float gi = gci_p[io], bt = bti_p[io];
;             const float dec = __expf(fminf(gi - gcj, 0.f));
;             const float lv = (i > j) ? acc[r] * bt * dec : 0.f, av = (i >= j) ? acc[r] * dec : 0.f;
;             if (mat == 0) Lm[i * 64 + j] = -lv;
;             else Aml[i * 72 + posj] = (bf16_t)f2bf(av); }
.LBB0_168:
	s_or_b64 exec, exec, s[20:21]
	v_sub_f32_e32 v0, v247, v18
	v_min_f32_e32 v0, 0, v0
	v_mul_f32_e32 v0, 0x3fb8aa3b, v0
	v_exp_f32_e32 v1, v0
	v_add_u32_e32 v0, 27, v17
	s_and_saveexec_b64 s[20:21], s[18:19]
	s_xor_b64 s[20:21], exec, s[20:21]
	s_cbranch_execz .LBB0_170
	v_mul_f32_e32 v1, v15, v1
	v_cmp_ge_i32_e32 vcc, v0, v148
	s_nop 1
	v_cndmask_b32_e32 v1, 0, v1, vcc
	v_bfe_u32 v2, v1, 16, 1
	v_add3_u32 v2, v1, v2, s96
	v_mad_u64_u32 v[0:1], s[22:23], v0, s31, v[122:123]
	ds_write_b16_d16_hi v0, v2
